# v61 + packed v_pk_add_f32 of the attention softmax row sums split into scalar v_add_f32 pairs (42 sites, bit-identical)
# baseline (speedup 1.0000x reference)
.LBB0_661:
	v_fma_f32 v0, v122, s46, -v166
	v_exp_f32_e32 v122, v0
	v_fma_f32 v0, v123, s46, -v166
	v_exp_f32_e32 v168, v0
	v_fma_f32 v0, v124, s46, -v166
	v_exp_f32_e32 v123, v0
	v_fma_f32 v0, v125, s46, -v166
	v_exp_f32_e32 v169, v0
	v_fma_f32 v0, v126, s46, -v166
	v_exp_f32_e32 v124, v0
	v_fma_f32 v0, v127, s46, -v166
	v_exp_f32_e32 v192, v0
	v_fma_f32 v0, v128, s46, -v166
	v_exp_f32_e32 v125, v0
	v_fma_f32 v0, v129, s46, -v166
	v_exp_f32_e32 v193, v0
	v_add_f32_e32 v126, v122, v168
	v_add_f32_e32 v127, v123, v169
	s_nop 0
	v_add_f32_e32 v0, v126, v127
	v_add_f32_e32 v126, v124, v192
	v_add_f32_e32 v127, v125, v193
	v_add_f32_e32 v167, 0, v0
	v_add_f32_e32 v194, v126, v126
	v_add_f32_e32 v195, v126, v127
	v_fma_f32 v126, v131, s46, -v166
	v_exp_f32_e32 v177, v126
	v_fma_f32 v126, v132, s46, -v166
	v_exp_f32_e32 v179, v126
	v_fma_f32 v126, v133, s46, -v166
	v_exp_f32_e32 v196, v126
	v_fma_f32 v126, v134, s46, -v166
	v_fma_f32 v0, v130, s46, -v166
	v_exp_f32_e32 v130, v126
	v_fma_f32 v126, v135, s46, -v166
	v_exp_f32_e32 v132, v126
	v_fma_f32 v126, v136, s46, -v166
	v_exp_f32_e32 v0, v0
	v_exp_f32_e32 v194, v126
	v_fma_f32 v126, v137, s46, -v166
	v_exp_f32_e32 v166, v126
	v_add_f32_e32 v131, v0, v177
	v_add_f32_e32 v133, v179, v196
	v_add_f32_e32 v126, v130, v132
	v_add_f32_e32 v127, v131, v133
	v_add_f32_e32 v128, v194, v166
	v_add_f32_e32 v129, v195, v167
	s_nop 0
	v_add_f32_e32 v126, v126, v128
	v_add_f32_e32 v127, v127, v129
	s_nop 0
	v_add_f32_e32 v126, v126, v127
	ds_bpermute_b32 v127, v155, v126
	s_nop 0
	s_waitcnt lgkmcnt(0)
	v_add_f32_e32 v126, v126, v127
	ds_bpermute_b32 v127, v176, v126
	s_waitcnt lgkmcnt(0)
	v_add_f32_e32 v126, v126, v127
	v_add_f32_e32 v160, v160, v126
	s_nop 1
	v_max_f32_e32 v126, v108, v109
	s_nop 0
	v_max_f32_e32 v127, v112, v113
	v_max3_f32 v126, v106, v107, v126
	v_max3_f32 v127, v110, v111, v127
	v_max3_f32 v126, v126, s51, v127
	s_nop 1
	v_max_f32_e32 v127, v116, v117
	s_nop 0
	v_max_f32_e32 v128, v120, v121
	v_max3_f32 v127, v114, v115, v127
	v_max3_f32 v128, v118, v119, v128
	v_max3_f32 v131, v126, v127, v128
	ds_bpermute_b32 v133, v155, v131
	v_cvt_pk_bf16_f32 v126, v122, v168
	v_cvt_pk_bf16_f32 v127, v123, v169
	v_cvt_pk_bf16_f32 v128, v124, v192
	v_cvt_pk_bf16_f32 v129, v125, v193
	s_waitcnt lgkmcnt(0)
	s_nop 0
	v_max_f32_e32 v131, v131, v133
	ds_bpermute_b32 v133, v176, v131
	v_cvt_pk_bf16_f32 v122, v0, v177
	v_cvt_pk_bf16_f32 v123, v179, v196
	v_cvt_pk_bf16_f32 v124, v130, v132
	v_add_f32_e32 v130, 0x41000000, v165
	s_waitcnt lgkmcnt(0)
	s_nop 0
	v_max_f32_e32 v0, v131, v133
	v_mul_f32_e32 v0, 0x3e16c740, v0
	v_cmp_gt_f32_e32 vcc, v0, v130
	v_cvt_pk_bf16_f32 v125, v194, v166
	s_cbranch_vccz .LBB0_663
	s_nop 0
	v_cndmask_b32_e32 v130, v165, v0, vcc
	v_sub_f32_e32 v0, v165, v130
	v_exp_f32_e32 v0, v0
	v_mov_b32_e32 v165, v130
	v_mul_f32_e32 v161, v161, v0
	v_pk_mul_f32 v[88:89], v[88:89], v[0:1] op_sel_hi:[1,0]
	v_pk_mul_f32 v[86:87], v[86:87], v[0:1] op_sel_hi:[1,0]
	v_pk_mul_f32 v[84:85], v[84:85], v[0:1] op_sel_hi:[1,0]
	v_pk_mul_f32 v[82:83], v[82:83], v[0:1] op_sel_hi:[1,0]
	v_pk_mul_f32 v[80:81], v[80:81], v[0:1] op_sel_hi:[1,0]
	v_pk_mul_f32 v[78:79], v[78:79], v[0:1] op_sel_hi:[1,0]
	v_pk_mul_f32 v[76:77], v[76:77], v[0:1] op_sel_hi:[1,0]
	v_pk_mul_f32 v[74:75], v[74:75], v[0:1] op_sel_hi:[1,0]
.LBB0_663:
	v_fma_f32 v0, v106, s46, -v165
	v_exp_f32_e32 v106, v0
	v_fma_f32 v0, v107, s46, -v165
	v_exp_f32_e32 v130, v0
	v_fma_f32 v0, v108, s46, -v165
	v_exp_f32_e32 v107, v0
	v_fma_f32 v0, v109, s46, -v165
	v_exp_f32_e32 v131, v0
	v_fma_f32 v0, v110, s46, -v165
	v_exp_f32_e32 v108, v0
	v_fma_f32 v0, v111, s46, -v165
	v_exp_f32_e32 v110, v0
	v_fma_f32 v0, v112, s46, -v165
	v_exp_f32_e32 v109, v0
	v_fma_f32 v0, v113, s46, -v165
	v_exp_f32_e32 v111, v0
	v_add_f32_e32 v112, v106, v130
	v_add_f32_e32 v113, v107, v131
	v_mov_b64_e32 v[168:169], v[164:165]
	v_add_f32_e32 v0, v112, v113
	v_add_f32_e32 v112, v108, v110
	v_add_f32_e32 v113, v109, v111
	v_add_f32_e32 v133, 0, v0
	v_add_f32_e32 v134, v112, v112
	v_add_f32_e32 v135, v112, v113
	v_fma_f32 v112, v115, s46, -v165
	v_exp_f32_e32 v136, v112
	v_fma_f32 v112, v116, s46, -v165
	v_fma_f32 v113, v119, s46, -v165
	v_fma_f32 v0, v114, s46, -v165
	v_exp_f32_e32 v137, v112
	v_fma_f32 v112, v117, s46, -v165
	v_exp_f32_e32 v114, v113
	v_fma_f32 v113, v120, s46, -v165
	v_exp_f32_e32 v0, v0
	v_exp_f32_e32 v164, v112
	v_fma_f32 v112, v118, s46, -v165
	v_exp_f32_e32 v134, v113
	v_fma_f32 v113, v121, s46, -v165
	v_exp_f32_e32 v112, v112
	v_exp_f32_e32 v132, v113
	v_add_f32_e32 v113, v0, v136
	v_add_f32_e32 v115, v137, v164
	v_add_f32_e32 v116, v112, v114
	v_add_f32_e32 v117, v113, v115
	v_add_f32_e32 v118, v134, v132
	v_add_f32_e32 v119, v135, v133
	v_cvt_pk_bf16_f32 v106, v106, v130
	v_cvt_pk_bf16_f32 v107, v107, v131
	v_cvt_pk_bf16_f32 v108, v108, v110
	v_cvt_pk_bf16_f32 v109, v109, v111
	v_cvt_pk_bf16_f32 v110, v0, v136
	s_nop 0
	v_add_f32_e32 v116, v116, v118
	v_add_f32_e32 v117, v117, v119
	v_cvt_pk_bf16_f32 v111, v137, v164
	v_cvt_pk_bf16_f32 v112, v112, v114
	s_nop 0
	v_add_f32_e32 v113, v116, v117
	ds_bpermute_b32 v115, v155, v113
	s_waitcnt lgkmcnt(0)
	v_add_f32_e32 v113, v113, v115
	ds_bpermute_b32 v115, v176, v113
	s_waitcnt lgkmcnt(0)
	v_add_f32_e32 v113, v113, v115
	v_add_f32_e32 v161, v161, v113
	v_cvt_pk_bf16_f32 v113, v134, v132
	ds_read_b64_tr_b16 v[116:117], v175 offset:18560
	ds_read_b64_tr_b16 v[114:115], v175 offset:17408
	ds_read_b64_tr_b16 v[118:119], v175 offset:17440
	ds_read_b64_tr_b16 v[120:121], v175 offset:18592
	s_waitcnt lgkmcnt(2)
	v_mfma_f32_16x16x32_bf16 v[102:105], v[114:117], v[126:129], v[102:105]
	v_mfma_f32_16x16x32_bf16 v[114:117], v[114:117], v[106:109], v[86:89]
	s_waitcnt lgkmcnt(0)
	v_mfma_f32_16x16x32_bf16 v[98:101], v[118:121], v[126:129], v[98:101]
	v_mfma_f32_16x16x32_bf16 v[118:121], v[118:121], v[106:109], v[82:85]
	s_nop 2
	ds_read_b64_tr_b16 v[82:83], v175 offset:17472
	ds_read_b64_tr_b16 v[84:85], v175 offset:18624
	s_waitcnt lgkmcnt(0)
	v_mfma_f32_16x16x32_bf16 v[130:133], v[82:85], v[106:109], v[78:81]
	s_nop 2
	ds_read_b64_tr_b16 v[78:79], v175 offset:17504
	ds_read_b64_tr_b16 v[80:81], v175 offset:18656
	v_mfma_f32_16x16x32_bf16 v[94:97], v[82:85], v[126:129], v[94:97]
	s_waitcnt lgkmcnt(0)
	v_mfma_f32_16x16x32_bf16 v[90:93], v[78:81], v[126:129], v[90:93]
	v_mfma_f32_16x16x32_bf16 v[106:109], v[78:81], v[106:109], v[74:77]
	s_nop 2
	ds_read_b64_tr_b16 v[76:77], v175 offset:27776
	ds_read_b64_tr_b16 v[74:75], v175 offset:26624
	ds_read_b64_tr_b16 v[78:79], v175 offset:26656
	ds_read_b64_tr_b16 v[80:81], v175 offset:27808
	s_add_i32 s4, s44, -2
	s_min_u32 s4, s4, s55
	s_waitcnt lgkmcnt(2)
	v_mfma_f32_16x16x32_bf16 v[86:89], v[74:77], v[122:125], v[102:105]
	s_lshl_b32 s4, s4, 6
	s_addk_i32 s4, 0xff00
	s_and_b64 s[48:49], s[40:41], exec
	v_mfma_f32_16x16x32_bf16 v[102:105], v[74:77], v[110:113], v[114:117]
	ds_read_b64_tr_b16 v[74:75], v175 offset:26688
	ds_read_b64_tr_b16 v[76:77], v175 offset:27840
	s_nop 0
	ds_read_b64_tr_b16 v[114:115], v175 offset:26720
	ds_read_b64_tr_b16 v[116:117], v175 offset:27872
	s_waitcnt lgkmcnt(0)
	v_mfma_f32_16x16x32_bf16 v[82:85], v[78:81], v[122:125], v[98:101]
	s_barrier
	s_waitcnt vmcnt(11)
	ds_write_b128 v170, v[38:41]
	s_waitcnt vmcnt(10)
	ds_write_b128 v171, v[42:45]
	s_waitcnt vmcnt(9)
	ds_write_b128 v172, v[46:49] offset:17408
	v_mfma_f32_16x16x32_bf16 v[98:101], v[78:81], v[110:113], v[118:121]
	s_waitcnt lgkmcnt(0)
	s_barrier
	v_mfma_f32_16x16x32_bf16 v[78:81], v[74:77], v[122:125], v[94:97]
	ds_read_b128 v[134:137], v173 offset:8832
	s_cselect_b32 s58, 0xc0, s4
	s_mul_i32 s52, s58, 0xc00
	v_mfma_f32_16x16x32_bf16 v[94:97], v[74:77], v[110:113], v[130:133]
	s_lshl_b64 s[48:49], s[58:59], 11
	ds_read_b128 v[118:121], v174 offset:1088
	s_mul_hi_u32 s4, s58, 0xc00
	v_mfma_f32_16x16x32_bf16 v[74:77], v[114:117], v[122:125], v[90:93]
	s_add_u32 s52, s42, s52
	s_addc_u32 s53, s43, s4
	v_lshl_add_u64 v[38:39], v[146:147], 1, s[52:53]
	v_mfma_f32_16x16x32_bf16 v[90:93], v[114:117], v[110:113], v[106:109]
	ds_read_b128 v[114:117], v174
	v_lshl_add_u64 v[42:43], v[148:149], 1, s[52:53]
	v_lshl_add_u64 v[38:39], v[140:141], 1, v[38:39]
	ds_read_b128 v[106:109], v173
	s_waitcnt lgkmcnt(0)
	v_mfma_f32_16x16x32_bf16 v[110:113], v[106:109], v[2:5], 0
	v_lshl_add_u64 v[42:43], v[142:143], 1, v[42:43]
	v_lshl_add_u64 v[46:47], v[162:163], 0, s[48:49]
	global_load_dwordx4 v[38:41], v[38:39], off
	v_mfma_f32_16x16x32_bf16 v[106:109], v[106:109], v[14:17], 0
	global_load_dwordx4 v[42:45], v[42:43], off
	ds_read_b128 v[130:133], v174 offset:8704
	global_load_dwordx4 v[46:49], v[46:47], off
	v_mfma_f32_16x16x32_bf16 v[110:113], v[114:117], v[6:9], v[110:113]
	ds_read_b128 v[192:195], v174 offset:9792
	v_mfma_f32_16x16x32_bf16 v[106:109], v[114:117], v[18:21], v[106:109]
	ds_read_b128 v[114:117], v173 offset:128
	s_waitcnt lgkmcnt(0)
	v_mfma_f32_16x16x32_bf16 v[122:125], v[114:117], v[10:13], v[110:113]
	s_nop 2
	ds_read_b128 v[110:113], v173 offset:1088
	s_nop 3
	s_nop 0
	v_mfma_f32_16x16x32_bf16 v[106:109], v[114:117], v[22:25], v[106:109]
	s_nop 0
	v_max_f32_e32 v0, v124, v125
	v_max3_f32 v0, v122, v123, v0
	s_waitcnt lgkmcnt(0)
	v_mfma_f32_16x16x32_bf16 v[114:117], v[110:113], v[2:5], 0
	v_mfma_f32_16x16x32_bf16 v[110:113], v[110:113], v[14:17], 0
	v_mfma_f32_16x16x32_bf16 v[114:117], v[118:121], v[6:9], v[114:117]
	v_mfma_f32_16x16x32_bf16 v[110:113], v[118:121], v[18:21], v[110:113]
	ds_read_b128 v[118:121], v173 offset:1216
	s_waitcnt lgkmcnt(0)
	v_mfma_f32_16x16x32_bf16 v[126:129], v[118:121], v[10:13], v[114:117]
	s_nop 3
	ds_read_b128 v[114:117], v173 offset:8704
	s_nop 2
	s_nop 0
	v_mfma_f32_16x16x32_bf16 v[110:113], v[118:121], v[22:25], v[110:113]
	s_nop 0
	v_max_f32_e32 v164, v128, v129
	v_max3_f32 v164, v126, v127, v164
	s_waitcnt lgkmcnt(0)
	v_mfma_f32_16x16x32_bf16 v[118:121], v[114:117], v[2:5], 0
	v_max3_f32 v0, v0, s51, v164
	v_mfma_f32_16x16x32_bf16 v[114:117], v[114:117], v[14:17], 0
	v_mfma_f32_16x16x32_bf16 v[118:121], v[130:133], v[6:9], v[118:121]
	v_mfma_f32_16x16x32_bf16 v[114:117], v[130:133], v[18:21], v[114:117]
	v_mfma_f32_16x16x32_bf16 v[130:133], v[134:137], v[10:13], v[118:121]
	s_nop 5
	ds_read_b128 v[118:121], v173 offset:9792
	v_mfma_f32_16x16x32_bf16 v[114:117], v[134:137], v[22:25], v[114:117]
	s_nop 1
	v_max_f32_e32 v164, v132, v133
	s_waitcnt lgkmcnt(0)
	v_mfma_f32_16x16x32_bf16 v[134:137], v[118:121], v[2:5], 0
	v_max3_f32 v164, v130, v131, v164
	v_mfma_f32_16x16x32_bf16 v[118:121], v[118:121], v[14:17], 0
	v_mfma_f32_16x16x32_bf16 v[134:137], v[192:195], v[6:9], v[134:137]
	v_mfma_f32_16x16x32_bf16 v[118:121], v[192:195], v[18:21], v[118:121]
	ds_read_b128 v[192:195], v173 offset:9920
	s_waitcnt lgkmcnt(0)
	v_mfma_f32_16x16x32_bf16 v[134:137], v[192:195], v[10:13], v[134:137]
	s_nop 7
	s_nop 1
	v_max_f32_e32 v166, v136, v137
	v_max3_f32 v166, v134, v135, v166
	v_max3_f32 v0, v0, v164, v166
	ds_bpermute_b32 v164, v155, v0
	v_mfma_f32_16x16x32_bf16 v[118:121], v[192:195], v[22:25], v[118:121]
	s_waitcnt lgkmcnt(0)
	s_nop 0
	v_max_f32_e32 v0, v0, v164
	ds_bpermute_b32 v164, v176, v0
	s_waitcnt lgkmcnt(0)
	s_nop 0
	v_max_f32_e32 v0, v0, v164
	v_mul_f32_e32 v0, 0x3e16c740, v0
	v_add_f32_e32 v164, 0x41000000, v168
	v_cmp_gt_f32_e32 vcc, v0, v164
	s_cbranch_vccz .LBB0_665
	s_nop 0
	v_cndmask_b32_e32 v166, v168, v0, vcc
	v_sub_f32_e32 v0, v168, v166
	v_exp_f32_e32 v0, v0
	v_mov_b32_e32 v167, v169
	v_mov_b32_e32 v165, v169
	v_mov_b32_e32 v168, v166
	v_mul_f32_e32 v160, v160, v0
	v_pk_mul_f32 v[88:89], v[88:89], v[0:1] op_sel_hi:[1,0]
	v_pk_mul_f32 v[86:87], v[86:87], v[0:1] op_sel_hi:[1,0]
	v_pk_mul_f32 v[84:85], v[84:85], v[0:1] op_sel_hi:[1,0]
	v_pk_mul_f32 v[82:83], v[82:83], v[0:1] op_sel_hi:[1,0]
	v_pk_mul_f32 v[80:81], v[80:81], v[0:1] op_sel_hi:[1,0]
	v_pk_mul_f32 v[78:79], v[78:79], v[0:1] op_sel_hi:[1,0]
	v_pk_mul_f32 v[76:77], v[76:77], v[0:1] op_sel_hi:[1,0]
	v_pk_mul_f32 v[74:75], v[74:75], v[0:1] op_sel_hi:[1,0]
	s_branch .LBB0_666

.LBB0_666:
	v_fma_f32 v0, v122, s46, -v168
	v_exp_f32_e32 v122, v0
	v_fma_f32 v0, v123, s46, -v168
	v_exp_f32_e32 v192, v0
	v_fma_f32 v0, v124, s46, -v168
	v_exp_f32_e32 v123, v0
	v_fma_f32 v0, v125, s46, -v168
	v_exp_f32_e32 v193, v0
	v_fma_f32 v0, v126, s46, -v168
	v_exp_f32_e32 v124, v0
	v_fma_f32 v0, v127, s46, -v168
	v_exp_f32_e32 v194, v0
	v_fma_f32 v0, v128, s46, -v168
	v_exp_f32_e32 v125, v0
	v_fma_f32 v0, v129, s46, -v168
	v_exp_f32_e32 v195, v0
	v_add_f32_e32 v126, v122, v192
	v_add_f32_e32 v127, v123, v193
	s_nop 0
	v_add_f32_e32 v0, v126, v127
	v_add_f32_e32 v126, v124, v194
	v_add_f32_e32 v127, v125, v195
	v_add_f32_e32 v169, 0, v0
	v_add_f32_e32 v196, v126, v126
	v_add_f32_e32 v197, v126, v127
	v_fma_f32 v126, v131, s46, -v168
	v_exp_f32_e32 v164, v126
	v_fma_f32 v126, v132, s46, -v168
	v_exp_f32_e32 v177, v126
	v_fma_f32 v126, v133, s46, -v168
	v_exp_f32_e32 v179, v126
	v_fma_f32 v126, v134, s46, -v168
	v_fma_f32 v0, v130, s46, -v168
	v_exp_f32_e32 v130, v126
	v_fma_f32 v126, v135, s46, -v168
	v_exp_f32_e32 v132, v126
	v_fma_f32 v126, v136, s46, -v168
	v_exp_f32_e32 v0, v0
	v_exp_f32_e32 v196, v126
	v_fma_f32 v126, v137, s46, -v168
	v_exp_f32_e32 v168, v126
	v_add_f32_e32 v131, v0, v164
	v_add_f32_e32 v133, v177, v179
	v_add_f32_e32 v126, v130, v132
	v_add_f32_e32 v127, v131, v133
	v_add_f32_e32 v128, v196, v168
	v_add_f32_e32 v129, v197, v169
	s_nop 0
	v_add_f32_e32 v126, v126, v128
	v_add_f32_e32 v127, v127, v129
	s_nop 0
	v_add_f32_e32 v126, v126, v127
	ds_bpermute_b32 v127, v155, v126
	s_nop 0
	s_waitcnt lgkmcnt(0)
	v_add_f32_e32 v126, v126, v127
	ds_bpermute_b32 v127, v176, v126
	s_waitcnt lgkmcnt(0)
	v_add_f32_e32 v126, v126, v127
	v_add_f32_e32 v160, v160, v126
	s_nop 1
	v_max_f32_e32 v126, v108, v109
	s_nop 0
	v_max_f32_e32 v127, v112, v113
	v_max3_f32 v126, v106, v107, v126
	v_max3_f32 v127, v110, v111, v127
	v_max3_f32 v126, v126, s51, v127
	s_nop 1
	v_max_f32_e32 v127, v116, v117
	s_nop 0
	v_max_f32_e32 v128, v120, v121
	v_max3_f32 v127, v114, v115, v127
	v_max3_f32 v128, v118, v119, v128
	v_max3_f32 v131, v126, v127, v128
	ds_bpermute_b32 v133, v155, v131
	v_cvt_pk_bf16_f32 v126, v122, v192
	v_cvt_pk_bf16_f32 v127, v123, v193
	v_cvt_pk_bf16_f32 v128, v124, v194
	v_cvt_pk_bf16_f32 v129, v125, v195
	s_waitcnt lgkmcnt(0)
	s_nop 0
	v_max_f32_e32 v131, v131, v133
	ds_bpermute_b32 v133, v176, v131
	v_cvt_pk_bf16_f32 v122, v0, v164
	v_cvt_pk_bf16_f32 v123, v177, v179
	v_cvt_pk_bf16_f32 v124, v130, v132
	v_add_f32_e32 v130, 0x41000000, v165
	s_waitcnt lgkmcnt(0)
	s_nop 0
	v_max_f32_e32 v0, v131, v133
	v_mul_f32_e32 v0, 0x3e16c740, v0
	v_cmp_gt_f32_e32 vcc, v0, v130
	v_cvt_pk_bf16_f32 v125, v196, v168
	s_cbranch_vccz .LBB0_668
	s_nop 0
	v_cndmask_b32_e32 v167, v165, v0, vcc
	v_sub_f32_e32 v0, v165, v167
	v_exp_f32_e32 v0, v0
	v_mov_b32_e32 v165, v167
	v_mul_f32_e32 v161, v161, v0
	v_pk_mul_f32 v[104:105], v[104:105], v[0:1] op_sel_hi:[1,0]
	v_pk_mul_f32 v[102:103], v[102:103], v[0:1] op_sel_hi:[1,0]
	v_pk_mul_f32 v[100:101], v[100:101], v[0:1] op_sel_hi:[1,0]
	v_pk_mul_f32 v[98:99], v[98:99], v[0:1] op_sel_hi:[1,0]
	v_pk_mul_f32 v[96:97], v[96:97], v[0:1] op_sel_hi:[1,0]
	v_pk_mul_f32 v[94:95], v[94:95], v[0:1] op_sel_hi:[1,0]
	v_pk_mul_f32 v[92:93], v[92:93], v[0:1] op_sel_hi:[1,0]
	v_pk_mul_f32 v[90:91], v[90:91], v[0:1] op_sel_hi:[1,0]
.LBB0_668:
	v_fma_f32 v0, v106, s46, -v165
	v_exp_f32_e32 v106, v0
	v_fma_f32 v0, v107, s46, -v165
	v_exp_f32_e32 v130, v0
	v_fma_f32 v0, v108, s46, -v165
	v_exp_f32_e32 v107, v0
	v_fma_f32 v0, v109, s46, -v165
	v_exp_f32_e32 v131, v0
	v_fma_f32 v0, v110, s46, -v165
	v_exp_f32_e32 v108, v0
	v_fma_f32 v0, v111, s46, -v165
	v_exp_f32_e32 v110, v0
	v_fma_f32 v0, v112, s46, -v165
	v_exp_f32_e32 v109, v0
	v_fma_f32 v0, v113, s46, -v165
	v_exp_f32_e32 v111, v0
	v_add_f32_e32 v112, v106, v130
	v_add_f32_e32 v113, v107, v131
	v_cvt_pk_bf16_f32 v106, v106, v130
	v_cvt_pk_bf16_f32 v107, v107, v131
	s_nop 0
	v_add_f32_e32 v0, v112, v113
	v_add_f32_e32 v112, v108, v110
	v_add_f32_e32 v113, v109, v111
	v_add_f32_e32 v133, 0, v0
	v_add_f32_e32 v134, v112, v112
	v_add_f32_e32 v135, v112, v113
	v_fma_f32 v112, v115, s46, -v165
	v_exp_f32_e32 v136, v112
	v_fma_f32 v112, v116, s46, -v165
	v_fma_f32 v113, v119, s46, -v165
	v_fma_f32 v0, v114, s46, -v165
	v_exp_f32_e32 v137, v112
	v_fma_f32 v112, v117, s46, -v165
	v_exp_f32_e32 v114, v113
	v_fma_f32 v113, v120, s46, -v165
	v_exp_f32_e32 v0, v0
	v_exp_f32_e32 v164, v112
	v_fma_f32 v112, v118, s46, -v165
	v_exp_f32_e32 v134, v113
	v_fma_f32 v113, v121, s46, -v165
	v_exp_f32_e32 v112, v112
	v_exp_f32_e32 v132, v113
	v_add_f32_e32 v113, v0, v136
	v_add_f32_e32 v115, v137, v164
	v_add_f32_e32 v116, v112, v114
	v_add_f32_e32 v117, v113, v115
	v_add_f32_e32 v118, v134, v132
	v_add_f32_e32 v119, v135, v133
	v_cvt_pk_bf16_f32 v108, v108, v110
	v_cvt_pk_bf16_f32 v109, v109, v111
	v_cvt_pk_bf16_f32 v110, v0, v136
	v_cvt_pk_bf16_f32 v111, v137, v164
	v_cvt_pk_bf16_f32 v112, v112, v114
	s_nop 0
	v_add_f32_e32 v116, v116, v118
	v_add_f32_e32 v117, v117, v119
	s_nop 0
	v_add_f32_e32 v113, v116, v117
	ds_bpermute_b32 v115, v155, v113
	s_waitcnt lgkmcnt(0)
	v_add_f32_e32 v113, v113, v115
	ds_bpermute_b32 v115, v176, v113
	s_waitcnt lgkmcnt(0)
	v_add_f32_e32 v113, v113, v115
	v_add_f32_e32 v161, v161, v113
	v_cvt_pk_bf16_f32 v113, v134, v132
	ds_read_b64_tr_b16 v[116:117], v175 offset:18560
	ds_read_b64_tr_b16 v[114:115], v175 offset:17408
	ds_read_b64_tr_b16 v[118:119], v175 offset:17440
	ds_read_b64_tr_b16 v[120:121], v175 offset:18592
	s_waitcnt lgkmcnt(2)
	v_mfma_f32_16x16x32_bf16 v[86:89], v[114:117], v[126:129], v[86:89]
	v_mfma_f32_16x16x32_bf16 v[102:105], v[114:117], v[106:109], v[102:105]
	ds_read_b64_tr_b16 v[114:115], v175 offset:17472
	ds_read_b64_tr_b16 v[116:117], v175 offset:18624
	s_waitcnt lgkmcnt(0)
	v_mfma_f32_16x16x32_bf16 v[78:81], v[114:117], v[126:129], v[78:81]
	v_mfma_f32_16x16x32_bf16 v[94:97], v[114:117], v[106:109], v[94:97]
	ds_read_b64_tr_b16 v[114:115], v175 offset:17504
	ds_read_b64_tr_b16 v[116:117], v175 offset:18656
	v_mfma_f32_16x16x32_bf16 v[82:85], v[118:121], v[126:129], v[82:85]
	v_mfma_f32_16x16x32_bf16 v[98:101], v[118:121], v[106:109], v[98:101]
	s_waitcnt lgkmcnt(0)
	v_mfma_f32_16x16x32_bf16 v[74:77], v[114:117], v[126:129], v[74:77]
	v_mfma_f32_16x16x32_bf16 v[90:93], v[114:117], v[106:109], v[90:93]
	ds_read_b64_tr_b16 v[108:109], v175 offset:27776
	ds_read_b64_tr_b16 v[106:107], v175 offset:26624
	ds_read_b64_tr_b16 v[114:115], v175 offset:26656
	ds_read_b64_tr_b16 v[116:117], v175 offset:27808
	s_add_i32 s4, s44, -1
	s_min_u32 s4, s4, s55
	s_waitcnt lgkmcnt(2)
	v_mfma_f32_16x16x32_bf16 v[86:89], v[106:109], v[122:125], v[86:89]
	s_lshl_b32 s4, s4, 6
	s_addk_i32 s4, 0xff00
	s_and_b64 s[48:49], s[40:41], exec
	v_mfma_f32_16x16x32_bf16 v[102:105], v[106:109], v[110:113], v[102:105]
	ds_read_b64_tr_b16 v[106:107], v175 offset:26688
	ds_read_b64_tr_b16 v[108:109], v175 offset:27840
	s_cselect_b32 s58, 0xc0, s4
	s_mul_i32 s52, s58, 0xc00
	s_waitcnt lgkmcnt(0)
	v_mfma_f32_16x16x32_bf16 v[78:81], v[106:109], v[122:125], v[78:81]
	s_lshl_b64 s[48:49], s[58:59], 11
	s_mul_hi_u32 s4, s58, 0xc00
	s_add_u32 s52, s42, s52
	v_mfma_f32_16x16x32_bf16 v[94:97], v[106:109], v[110:113], v[94:97]
	ds_read_b64_tr_b16 v[106:107], v175 offset:26720
	ds_read_b64_tr_b16 v[108:109], v175 offset:27872
	s_waitcnt lgkmcnt(0)
	s_barrier
	v_mfma_f32_16x16x32_bf16 v[74:77], v[106:109], v[122:125], v[74:77]
	s_waitcnt vmcnt(11)
	ds_write_b128 v170, v[50:53]
	s_waitcnt vmcnt(10)
	ds_write_b128 v171, v[54:57]
	s_waitcnt vmcnt(9)
	ds_write_b128 v172, v[58:61] offset:17408
	s_waitcnt lgkmcnt(0)
	v_mfma_f32_16x16x32_bf16 v[90:93], v[106:109], v[110:113], v[90:93]
	s_barrier
	ds_read_b128 v[106:109], v173
	ds_read_b128 v[134:137], v173 offset:8832
	v_mfma_f32_16x16x32_bf16 v[82:85], v[114:117], v[122:125], v[82:85]
	ds_read_b128 v[118:121], v174 offset:1088
	s_addc_u32 s53, s43, s4
	v_lshl_add_u64 v[50:51], v[146:147], 1, s[52:53]
	v_mfma_f32_16x16x32_bf16 v[98:101], v[114:117], v[110:113], v[98:101]
	ds_read_b128 v[114:117], v174
	v_lshl_add_u64 v[54:55], v[148:149], 1, s[52:53]
	v_lshl_add_u64 v[50:51], v[140:141], 1, v[50:51]
	s_waitcnt lgkmcnt(3)
	v_mfma_f32_16x16x32_bf16 v[110:113], v[106:109], v[2:5], 0
	v_lshl_add_u64 v[54:55], v[142:143], 1, v[54:55]
	v_lshl_add_u64 v[58:59], v[162:163], 0, s[48:49]
	global_load_dwordx4 v[50:53], v[50:51], off
	v_mfma_f32_16x16x32_bf16 v[106:109], v[106:109], v[14:17], 0
	global_load_dwordx4 v[54:57], v[54:55], off
	ds_read_b128 v[130:133], v174 offset:8704
	global_load_dwordx4 v[58:61], v[58:59], off
	s_waitcnt lgkmcnt(1)
	v_mfma_f32_16x16x32_bf16 v[110:113], v[114:117], v[6:9], v[110:113]
	ds_read_b128 v[192:195], v174 offset:9792
	v_mfma_f32_16x16x32_bf16 v[106:109], v[114:117], v[18:21], v[106:109]
	ds_read_b128 v[114:117], v173 offset:128
	s_waitcnt lgkmcnt(0)
	v_mfma_f32_16x16x32_bf16 v[122:125], v[114:117], v[10:13], v[110:113]
	s_nop 2
	ds_read_b128 v[110:113], v173 offset:1088
	s_nop 3
	s_nop 0
	v_mfma_f32_16x16x32_bf16 v[106:109], v[114:117], v[22:25], v[106:109]
	s_nop 0
	v_max_f32_e32 v0, v124, v125
	v_max3_f32 v0, v122, v123, v0
	s_waitcnt lgkmcnt(0)
	v_mfma_f32_16x16x32_bf16 v[114:117], v[110:113], v[2:5], 0
	v_mfma_f32_16x16x32_bf16 v[110:113], v[110:113], v[14:17], 0
	v_mfma_f32_16x16x32_bf16 v[114:117], v[118:121], v[6:9], v[114:117]
	v_mfma_f32_16x16x32_bf16 v[110:113], v[118:121], v[18:21], v[110:113]
	ds_read_b128 v[118:121], v173 offset:1216
	s_waitcnt lgkmcnt(0)
	v_mfma_f32_16x16x32_bf16 v[126:129], v[118:121], v[10:13], v[114:117]
	s_nop 3
	ds_read_b128 v[114:117], v173 offset:8704
	s_nop 2
	s_nop 0
	v_mfma_f32_16x16x32_bf16 v[110:113], v[118:121], v[22:25], v[110:113]
	s_nop 0
	v_max_f32_e32 v164, v128, v129
	v_max3_f32 v164, v126, v127, v164
	s_waitcnt lgkmcnt(0)
	v_mfma_f32_16x16x32_bf16 v[118:121], v[114:117], v[2:5], 0
	v_max3_f32 v0, v0, s51, v164
	v_mfma_f32_16x16x32_bf16 v[114:117], v[114:117], v[14:17], 0
	v_mfma_f32_16x16x32_bf16 v[118:121], v[130:133], v[6:9], v[118:121]
	v_mfma_f32_16x16x32_bf16 v[114:117], v[130:133], v[18:21], v[114:117]
	v_mfma_f32_16x16x32_bf16 v[130:133], v[134:137], v[10:13], v[118:121]
	s_nop 5
	ds_read_b128 v[118:121], v173 offset:9792
	v_mfma_f32_16x16x32_bf16 v[114:117], v[134:137], v[22:25], v[114:117]
	s_nop 1
	v_max_f32_e32 v164, v132, v133
	s_waitcnt lgkmcnt(0)
	v_mfma_f32_16x16x32_bf16 v[134:137], v[118:121], v[2:5], 0
	v_max3_f32 v164, v130, v131, v164
	v_mfma_f32_16x16x32_bf16 v[118:121], v[118:121], v[14:17], 0
	v_mfma_f32_16x16x32_bf16 v[134:137], v[192:195], v[6:9], v[134:137]
	v_mfma_f32_16x16x32_bf16 v[118:121], v[192:195], v[18:21], v[118:121]
	ds_read_b128 v[192:195], v173 offset:9920
	s_waitcnt lgkmcnt(0)
	v_mfma_f32_16x16x32_bf16 v[134:137], v[192:195], v[10:13], v[134:137]
	s_nop 7
	s_nop 1
	v_max_f32_e32 v168, v136, v137
	v_max3_f32 v168, v134, v135, v168
	v_max3_f32 v0, v0, v164, v168
	ds_bpermute_b32 v164, v155, v0
	v_mfma_f32_16x16x32_bf16 v[118:121], v[192:195], v[22:25], v[118:121]
	s_waitcnt lgkmcnt(0)
	s_nop 0
	v_max_f32_e32 v0, v0, v164
	ds_bpermute_b32 v164, v176, v0
	s_waitcnt lgkmcnt(0)
	s_nop 0
	v_max_f32_e32 v0, v0, v164
	v_mul_f32_e32 v0, 0x3e16c740, v0
	v_add_f32_e32 v164, 0x41000000, v166
	v_cmp_gt_f32_e32 vcc, v0, v164
	s_cbranch_vccz .LBB0_670
	s_nop 0
	v_cndmask_b32_e32 v168, v166, v0, vcc
	v_sub_f32_e32 v0, v166, v168
	v_exp_f32_e32 v0, v0
	v_mov_b32_e32 v169, v167
	v_mov_b32_e32 v165, v167
	v_mov_b32_e32 v166, v168
	v_mul_f32_e32 v160, v160, v0
	v_pk_mul_f32 v[88:89], v[88:89], v[0:1] op_sel_hi:[1,0]
	v_pk_mul_f32 v[86:87], v[86:87], v[0:1] op_sel_hi:[1,0]
	v_pk_mul_f32 v[84:85], v[84:85], v[0:1] op_sel_hi:[1,0]
	v_pk_mul_f32 v[82:83], v[82:83], v[0:1] op_sel_hi:[1,0]
	v_pk_mul_f32 v[80:81], v[80:81], v[0:1] op_sel_hi:[1,0]
	v_pk_mul_f32 v[78:79], v[78:79], v[0:1] op_sel_hi:[1,0]
	v_pk_mul_f32 v[76:77], v[76:77], v[0:1] op_sel_hi:[1,0]
	v_pk_mul_f32 v[74:75], v[74:75], v[0:1] op_sel_hi:[1,0]
	s_branch .LBB0_671

.LBB0_671:
	v_fma_f32 v0, v122, s46, -v166
	v_exp_f32_e32 v122, v0
	v_fma_f32 v0, v123, s46, -v166
	v_exp_f32_e32 v192, v0
	v_fma_f32 v0, v124, s46, -v166
	v_exp_f32_e32 v123, v0
	v_fma_f32 v0, v125, s46, -v166
	v_exp_f32_e32 v193, v0
	v_fma_f32 v0, v126, s46, -v166
	v_exp_f32_e32 v124, v0
	v_fma_f32 v0, v127, s46, -v166
	v_exp_f32_e32 v194, v0
	v_fma_f32 v0, v128, s46, -v166
	v_exp_f32_e32 v125, v0
	v_fma_f32 v0, v129, s46, -v166
	v_exp_f32_e32 v195, v0
	v_add_f32_e32 v126, v122, v192
	v_add_f32_e32 v127, v123, v193
	s_nop 0
	v_add_f32_e32 v0, v126, v127
	v_add_f32_e32 v126, v124, v194
	v_add_f32_e32 v127, v125, v195
	v_add_f32_e32 v167, 0, v0
	v_add_f32_e32 v196, v126, v126
	v_add_f32_e32 v197, v126, v127
	v_fma_f32 v126, v131, s46, -v166
	v_exp_f32_e32 v164, v126
	v_fma_f32 v126, v132, s46, -v166
	v_exp_f32_e32 v177, v126
	v_fma_f32 v126, v133, s46, -v166
	v_exp_f32_e32 v179, v126
	v_fma_f32 v126, v134, s46, -v166
	v_fma_f32 v0, v130, s46, -v166
	v_exp_f32_e32 v130, v126
	v_fma_f32 v126, v135, s46, -v166
	v_exp_f32_e32 v132, v126
	v_fma_f32 v126, v136, s46, -v166
	v_exp_f32_e32 v0, v0
	v_exp_f32_e32 v196, v126
	v_fma_f32 v126, v137, s46, -v166
	v_exp_f32_e32 v166, v126
	v_add_f32_e32 v131, v0, v164
	v_add_f32_e32 v133, v177, v179
	v_add_f32_e32 v126, v130, v132
	v_add_f32_e32 v127, v131, v133
	v_add_f32_e32 v128, v196, v166
	v_add_f32_e32 v129, v197, v167
	s_nop 0
	v_add_f32_e32 v126, v126, v128
	v_add_f32_e32 v127, v127, v129
	s_nop 0
	v_add_f32_e32 v126, v126, v127
	ds_bpermute_b32 v127, v155, v126
	s_nop 0
	s_waitcnt lgkmcnt(0)
	v_add_f32_e32 v126, v126, v127
	ds_bpermute_b32 v127, v176, v126
	s_waitcnt lgkmcnt(0)
	v_add_f32_e32 v126, v126, v127
	v_add_f32_e32 v160, v160, v126
	s_nop 1
	v_max_f32_e32 v126, v108, v109
	s_nop 0
	v_max_f32_e32 v127, v112, v113
	v_max3_f32 v126, v106, v107, v126
	v_max3_f32 v127, v110, v111, v127
	v_max3_f32 v126, v126, s51, v127
	s_nop 1
	v_max_f32_e32 v127, v116, v117
	s_nop 0
	v_max_f32_e32 v128, v120, v121
	v_max3_f32 v127, v114, v115, v127
	v_max3_f32 v128, v118, v119, v128
	v_max3_f32 v131, v126, v127, v128
	ds_bpermute_b32 v133, v155, v131
	v_cvt_pk_bf16_f32 v126, v122, v192
	v_cvt_pk_bf16_f32 v127, v123, v193
	v_cvt_pk_bf16_f32 v128, v124, v194
	v_cvt_pk_bf16_f32 v129, v125, v195
	s_waitcnt lgkmcnt(0)
	s_nop 0
	v_max_f32_e32 v131, v131, v133
	ds_bpermute_b32 v133, v176, v131
	v_cvt_pk_bf16_f32 v122, v0, v164
	v_cvt_pk_bf16_f32 v123, v177, v179
	v_cvt_pk_bf16_f32 v124, v130, v132
	v_add_f32_e32 v130, 0x41000000, v165
	s_waitcnt lgkmcnt(0)
	s_nop 0
	v_max_f32_e32 v0, v131, v133
	v_mul_f32_e32 v0, 0x3e16c740, v0
	v_cmp_gt_f32_e32 vcc, v0, v130
	v_cvt_pk_bf16_f32 v125, v196, v166
	s_cbranch_vccz .LBB0_673
	s_nop 0
	v_cndmask_b32_e32 v169, v165, v0, vcc
	v_sub_f32_e32 v0, v165, v169
	v_exp_f32_e32 v0, v0
	v_mov_b32_e32 v165, v169
	v_mul_f32_e32 v161, v161, v0
	v_pk_mul_f32 v[104:105], v[104:105], v[0:1] op_sel_hi:[1,0]
	v_pk_mul_f32 v[102:103], v[102:103], v[0:1] op_sel_hi:[1,0]
	v_pk_mul_f32 v[100:101], v[100:101], v[0:1] op_sel_hi:[1,0]
	v_pk_mul_f32 v[98:99], v[98:99], v[0:1] op_sel_hi:[1,0]
	v_pk_mul_f32 v[96:97], v[96:97], v[0:1] op_sel_hi:[1,0]
	v_pk_mul_f32 v[94:95], v[94:95], v[0:1] op_sel_hi:[1,0]
	v_pk_mul_f32 v[92:93], v[92:93], v[0:1] op_sel_hi:[1,0]
	v_pk_mul_f32 v[90:91], v[90:91], v[0:1] op_sel_hi:[1,0]
.LBB0_673:
	v_fma_f32 v0, v106, s46, -v165
	v_exp_f32_e32 v106, v0
	v_fma_f32 v0, v107, s46, -v165
	v_exp_f32_e32 v130, v0
	v_fma_f32 v0, v108, s46, -v165
	v_exp_f32_e32 v107, v0
	v_fma_f32 v0, v109, s46, -v165
	v_exp_f32_e32 v131, v0
	v_fma_f32 v0, v110, s46, -v165
	v_exp_f32_e32 v108, v0
	v_fma_f32 v0, v111, s46, -v165
	v_exp_f32_e32 v110, v0
	v_fma_f32 v0, v112, s46, -v165
	v_exp_f32_e32 v109, v0
	v_fma_f32 v0, v113, s46, -v165
	v_exp_f32_e32 v111, v0
	v_add_f32_e32 v112, v106, v130
	v_add_f32_e32 v113, v107, v131
	v_cvt_pk_bf16_f32 v106, v106, v130
	v_cvt_pk_bf16_f32 v107, v107, v131
	s_nop 0
	v_add_f32_e32 v0, v112, v113
	v_add_f32_e32 v112, v108, v110
	v_add_f32_e32 v113, v109, v111
	v_add_f32_e32 v133, 0, v0
	v_add_f32_e32 v134, v112, v112
	v_add_f32_e32 v135, v112, v113
	v_fma_f32 v112, v115, s46, -v165
	v_exp_f32_e32 v136, v112
	v_fma_f32 v112, v116, s46, -v165
	v_fma_f32 v113, v119, s46, -v165
	v_fma_f32 v0, v114, s46, -v165
	v_exp_f32_e32 v137, v112
	v_fma_f32 v112, v117, s46, -v165
	v_exp_f32_e32 v114, v113
	v_fma_f32 v113, v120, s46, -v165
	v_exp_f32_e32 v0, v0
	v_exp_f32_e32 v164, v112
	v_fma_f32 v112, v118, s46, -v165
	v_exp_f32_e32 v134, v113
	v_fma_f32 v113, v121, s46, -v165
	v_exp_f32_e32 v112, v112
	v_exp_f32_e32 v132, v113
	v_add_f32_e32 v113, v0, v136
	v_add_f32_e32 v115, v137, v164
	v_add_f32_e32 v116, v112, v114
	v_add_f32_e32 v117, v113, v115
	v_add_f32_e32 v118, v134, v132
	v_add_f32_e32 v119, v135, v133
	v_cvt_pk_bf16_f32 v108, v108, v110
	v_cvt_pk_bf16_f32 v109, v109, v111
	v_cvt_pk_bf16_f32 v110, v0, v136
	v_cvt_pk_bf16_f32 v111, v137, v164
	v_cvt_pk_bf16_f32 v112, v112, v114
	s_nop 0
	v_add_f32_e32 v116, v116, v118
	v_add_f32_e32 v117, v117, v119
	s_nop 0
	v_add_f32_e32 v113, v116, v117
	ds_bpermute_b32 v115, v155, v113
	s_waitcnt lgkmcnt(0)
	v_add_f32_e32 v113, v113, v115
	ds_bpermute_b32 v115, v176, v113
	s_waitcnt lgkmcnt(0)
	v_add_f32_e32 v113, v113, v115
	v_add_f32_e32 v161, v161, v113
	v_cvt_pk_bf16_f32 v113, v134, v132
	ds_read_b64_tr_b16 v[116:117], v175 offset:18560
	ds_read_b64_tr_b16 v[114:115], v175 offset:17408
	ds_read_b64_tr_b16 v[118:119], v175 offset:17440
	ds_read_b64_tr_b16 v[120:121], v175 offset:18592
	s_waitcnt lgkmcnt(2)
	v_mfma_f32_16x16x32_bf16 v[86:89], v[114:117], v[126:129], v[86:89]
	v_mfma_f32_16x16x32_bf16 v[102:105], v[114:117], v[106:109], v[102:105]
	ds_read_b64_tr_b16 v[114:115], v175 offset:17472
	ds_read_b64_tr_b16 v[116:117], v175 offset:18624
	s_waitcnt lgkmcnt(0)
	v_mfma_f32_16x16x32_bf16 v[78:81], v[114:117], v[126:129], v[78:81]
	v_mfma_f32_16x16x32_bf16 v[94:97], v[114:117], v[106:109], v[94:97]
	ds_read_b64_tr_b16 v[114:115], v175 offset:17504
	ds_read_b64_tr_b16 v[116:117], v175 offset:18656
	v_mfma_f32_16x16x32_bf16 v[82:85], v[118:121], v[126:129], v[82:85]
	v_mfma_f32_16x16x32_bf16 v[98:101], v[118:121], v[106:109], v[98:101]
	s_waitcnt lgkmcnt(0)
	v_mfma_f32_16x16x32_bf16 v[74:77], v[114:117], v[126:129], v[74:77]
	v_mfma_f32_16x16x32_bf16 v[90:93], v[114:117], v[106:109], v[90:93]
	ds_read_b64_tr_b16 v[108:109], v175 offset:27776
	ds_read_b64_tr_b16 v[106:107], v175 offset:26624
	ds_read_b64_tr_b16 v[114:115], v175 offset:26656
	ds_read_b64_tr_b16 v[116:117], v175 offset:27808
	s_min_u32 s4, s44, s55
	s_lshl_b32 s4, s4, 6
	s_waitcnt lgkmcnt(2)
	v_mfma_f32_16x16x32_bf16 v[86:89], v[106:109], v[122:125], v[86:89]
	s_addk_i32 s4, 0xff00
	s_and_b64 s[48:49], s[40:41], exec
	s_cselect_b32 s58, 0xc0, s4
	v_mfma_f32_16x16x32_bf16 v[102:105], v[106:109], v[110:113], v[102:105]
	ds_read_b64_tr_b16 v[106:107], v175 offset:26688
	ds_read_b64_tr_b16 v[108:109], v175 offset:27840
	s_mul_i32 s52, s58, 0xc00
	s_lshl_b64 s[48:49], s[58:59], 11
	s_waitcnt lgkmcnt(0)
	v_mfma_f32_16x16x32_bf16 v[78:81], v[106:109], v[122:125], v[78:81]
	s_mul_hi_u32 s4, s58, 0xc00
	s_add_u32 s52, s42, s52
	s_addc_u32 s53, s43, s4
	v_mfma_f32_16x16x32_bf16 v[94:97], v[106:109], v[110:113], v[94:97]
	ds_read_b64_tr_b16 v[106:107], v175 offset:26720
	ds_read_b64_tr_b16 v[108:109], v175 offset:27872
	s_waitcnt lgkmcnt(0)
	s_barrier
	v_mfma_f32_16x16x32_bf16 v[74:77], v[106:109], v[122:125], v[74:77]
	s_waitcnt vmcnt(11)
	ds_write_b128 v170, v[62:65]
	s_waitcnt vmcnt(10)
	ds_write_b128 v171, v[66:69]
	s_waitcnt vmcnt(9)
	ds_write_b128 v172, v[70:73] offset:17408
	s_waitcnt lgkmcnt(0)
	v_mfma_f32_16x16x32_bf16 v[90:93], v[106:109], v[110:113], v[90:93]
	s_barrier
	ds_read_b128 v[106:109], v173
	ds_read_b128 v[134:137], v173 offset:8832
	v_mfma_f32_16x16x32_bf16 v[82:85], v[114:117], v[122:125], v[82:85]
	ds_read_b128 v[118:121], v174 offset:1088
	v_lshl_add_u64 v[62:63], v[146:147], 1, s[52:53]
	v_lshl_add_u64 v[66:67], v[148:149], 1, s[52:53]
	v_mfma_f32_16x16x32_bf16 v[98:101], v[114:117], v[110:113], v[98:101]
	ds_read_b128 v[114:117], v174
	v_lshl_add_u64 v[62:63], v[140:141], 1, v[62:63]
	v_lshl_add_u64 v[66:67], v[142:143], 1, v[66:67]
	s_waitcnt lgkmcnt(3)
	v_mfma_f32_16x16x32_bf16 v[110:113], v[106:109], v[2:5], 0
	v_lshl_add_u64 v[70:71], v[162:163], 0, s[48:49]
	global_load_dwordx4 v[62:65], v[62:63], off
	ds_read_b128 v[130:133], v174 offset:8704
	v_mfma_f32_16x16x32_bf16 v[106:109], v[106:109], v[14:17], 0
	global_load_dwordx4 v[66:69], v[66:67], off
	ds_read_b128 v[192:195], v174 offset:9792
	global_load_dwordx4 v[70:73], v[70:71], off
	s_waitcnt lgkmcnt(2)
	v_mfma_f32_16x16x32_bf16 v[110:113], v[114:117], v[6:9], v[110:113]
	v_mfma_f32_16x16x32_bf16 v[106:109], v[114:117], v[18:21], v[106:109]
	ds_read_b128 v[114:117], v173 offset:128
	s_waitcnt lgkmcnt(0)
	v_mfma_f32_16x16x32_bf16 v[122:125], v[114:117], v[10:13], v[110:113]
	s_nop 3
	ds_read_b128 v[110:113], v173 offset:1088
	s_nop 2
	s_nop 0
	v_mfma_f32_16x16x32_bf16 v[106:109], v[114:117], v[22:25], v[106:109]
	s_nop 0
	v_max_f32_e32 v0, v124, v125
	v_max3_f32 v0, v122, v123, v0
	s_waitcnt lgkmcnt(0)
	v_mfma_f32_16x16x32_bf16 v[114:117], v[110:113], v[2:5], 0
	v_mfma_f32_16x16x32_bf16 v[110:113], v[110:113], v[14:17], 0
	v_mfma_f32_16x16x32_bf16 v[114:117], v[118:121], v[6:9], v[114:117]
	v_mfma_f32_16x16x32_bf16 v[110:113], v[118:121], v[18:21], v[110:113]
	ds_read_b128 v[118:121], v173 offset:1216
	s_waitcnt lgkmcnt(0)
	v_mfma_f32_16x16x32_bf16 v[126:129], v[118:121], v[10:13], v[114:117]
	s_nop 3
	ds_read_b128 v[114:117], v173 offset:8704
	s_nop 2
	s_nop 0
	v_mfma_f32_16x16x32_bf16 v[110:113], v[118:121], v[22:25], v[110:113]
	s_nop 0
	v_max_f32_e32 v164, v128, v129
	v_max3_f32 v164, v126, v127, v164
	s_waitcnt lgkmcnt(0)
	v_mfma_f32_16x16x32_bf16 v[118:121], v[114:117], v[2:5], 0
	v_max3_f32 v0, v0, s51, v164
	v_mfma_f32_16x16x32_bf16 v[114:117], v[114:117], v[14:17], 0
	v_mfma_f32_16x16x32_bf16 v[118:121], v[130:133], v[6:9], v[118:121]
	v_mfma_f32_16x16x32_bf16 v[114:117], v[130:133], v[18:21], v[114:117]
	v_mfma_f32_16x16x32_bf16 v[130:133], v[134:137], v[10:13], v[118:121]
	s_nop 5
	ds_read_b128 v[118:121], v173 offset:9792
	v_mfma_f32_16x16x32_bf16 v[114:117], v[134:137], v[22:25], v[114:117]
	s_nop 1
	v_max_f32_e32 v164, v132, v133
	s_waitcnt lgkmcnt(0)
	v_mfma_f32_16x16x32_bf16 v[134:137], v[118:121], v[2:5], 0
	v_max3_f32 v164, v130, v131, v164
	v_mfma_f32_16x16x32_bf16 v[118:121], v[118:121], v[14:17], 0
	v_mfma_f32_16x16x32_bf16 v[134:137], v[192:195], v[6:9], v[134:137]
	v_mfma_f32_16x16x32_bf16 v[118:121], v[192:195], v[18:21], v[118:121]
	ds_read_b128 v[192:195], v173 offset:9920
	s_waitcnt lgkmcnt(0)
	v_mfma_f32_16x16x32_bf16 v[134:137], v[192:195], v[10:13], v[134:137]
	s_nop 7
	s_nop 1
	v_max_f32_e32 v166, v136, v137
	v_max3_f32 v166, v134, v135, v166
	v_max3_f32 v0, v0, v164, v166
	ds_bpermute_b32 v164, v155, v0
	v_mfma_f32_16x16x32_bf16 v[118:121], v[192:195], v[22:25], v[118:121]
	s_waitcnt lgkmcnt(0)
	s_nop 0
	v_max_f32_e32 v0, v0, v164
	ds_bpermute_b32 v164, v176, v0
	s_waitcnt lgkmcnt(0)
	s_nop 0
	v_max_f32_e32 v0, v0, v164
	v_mul_f32_e32 v0, 0x3e16c740, v0
	v_add_f32_e32 v164, 0x41000000, v168
	v_cmp_gt_f32_e32 vcc, v0, v164
	s_cbranch_vccz .LBB0_675
	s_nop 0
	v_cndmask_b32_e32 v166, v168, v0, vcc
	v_sub_f32_e32 v0, v168, v166
	v_exp_f32_e32 v0, v0
	v_mov_b32_e32 v167, v169
	v_mov_b32_e32 v165, v169
	v_mov_b32_e32 v168, v166
	v_mul_f32_e32 v160, v160, v0
	v_pk_mul_f32 v[88:89], v[88:89], v[0:1] op_sel_hi:[1,0]
	v_pk_mul_f32 v[86:87], v[86:87], v[0:1] op_sel_hi:[1,0]
	v_pk_mul_f32 v[84:85], v[84:85], v[0:1] op_sel_hi:[1,0]
	v_pk_mul_f32 v[82:83], v[82:83], v[0:1] op_sel_hi:[1,0]
	v_pk_mul_f32 v[80:81], v[80:81], v[0:1] op_sel_hi:[1,0]
	v_pk_mul_f32 v[78:79], v[78:79], v[0:1] op_sel_hi:[1,0]
	v_pk_mul_f32 v[76:77], v[76:77], v[0:1] op_sel_hi:[1,0]
	v_pk_mul_f32 v[74:75], v[74:75], v[0:1] op_sel_hi:[1,0]
	s_branch .LBB0_676

.LBB0_1074:
	v_add_f32_e32 v3, v3, v194
	v_add_f32_e32 v195, v0, v3
	v_fmamk_f32 v0, v124, 0x3e38aa3b, v196
	v_exp_f32_e32 v124, v0
	v_fmamk_f32 v0, v125, 0x3e38aa3b, v196
	v_exp_f32_e32 v200, v0
	v_fmamk_f32 v0, v126, 0x3e38aa3b, v196
	v_exp_f32_e32 v125, v0
	v_fmamk_f32 v0, v127, 0x3e38aa3b, v196
	v_exp_f32_e32 v201, v0
	v_fmamk_f32 v3, v133, 0x3e38aa3b, v196
	v_exp_f32_e32 v3, v3
	v_add_f32_e32 v126, v124, v200
	v_add_f32_e32 v127, v125, v201
	s_nop 0
	v_add_f32_e32 v0, v126, v127
	v_add_f32_e32 v197, 0, v0
	v_fmamk_f32 v0, v128, 0x3e38aa3b, v196
	v_exp_f32_e32 v126, v0
	v_fmamk_f32 v0, v129, 0x3e38aa3b, v196
	v_exp_f32_e32 v202, v0
	v_fmamk_f32 v0, v130, 0x3e38aa3b, v196
	v_exp_f32_e32 v127, v0
	v_fmamk_f32 v0, v131, 0x3e38aa3b, v196
	v_exp_f32_e32 v203, v0
	v_fmamk_f32 v0, v132, 0x3e38aa3b, v196
	v_exp_f32_e32 v0, v0
	v_add_f32_e32 v128, v126, v202
	v_add_f32_e32 v129, v127, v203
	s_nop 0
	v_add_f32_e32 v204, v128, v128
	v_add_f32_e32 v205, v128, v129
	v_fmamk_f32 v128, v134, 0x3e38aa3b, v196
	v_exp_f32_e32 v194, v128
	v_fmamk_f32 v128, v135, 0x3e38aa3b, v196
	v_exp_f32_e32 v199, v128
	v_fmamk_f32 v128, v136, 0x3e38aa3b, v196
	v_exp_f32_e32 v132, v128
	v_fmamk_f32 v128, v137, 0x3e38aa3b, v196
	v_exp_f32_e32 v134, v128
	v_fmamk_f32 v128, v138, 0x3e38aa3b, v196
	v_fmac_f32_e32 v196, 0x3e38aa3b, v139
	v_exp_f32_e32 v204, v128
	v_exp_f32_e32 v196, v196
	v_add_f32_e32 v133, v0, v3
	v_add_f32_e32 v135, v194, v199
	v_add_f32_e32 v128, v132, v134
	v_add_f32_e32 v129, v133, v135
	v_add_f32_e32 v130, v204, v196
	v_add_f32_e32 v131, v205, v197
	s_nop 0
	v_add_f32_e32 v128, v128, v130
	v_add_f32_e32 v129, v129, v131
	s_nop 0
	v_add_f32_e32 v128, v128, v129
	ds_bpermute_b32 v129, v198, v128
	s_waitcnt lgkmcnt(0)
	v_add_f32_e32 v128, v128, v129
	ds_bpermute_b32 v129, v179, v128
	s_waitcnt lgkmcnt(0)
	v_add_f32_e32 v133, v128, v129
	v_cvt_pk_bf16_f32 v128, v124, v200
	v_cvt_pk_bf16_f32 v129, v125, v201
	v_cvt_pk_bf16_f32 v130, v126, v202
	v_cvt_pk_bf16_f32 v131, v127, v203
	v_cvt_pk_bf16_f32 v124, v0, v3
	v_cvt_pk_bf16_f32 v125, v194, v199
	v_add_f32_e32 v194, v2, v133
	v_cvt_pk_bf16_f32 v126, v132, v134
	v_cvt_pk_bf16_f32 v127, v204, v196
	ds_read_b64_tr_b16 v[134:135], v174 offset:18560
	ds_read_b64_tr_b16 v[132:133], v174 offset:17408
	ds_read_b64_tr_b16 v[136:137], v174 offset:17440
	ds_read_b64_tr_b16 v[138:139], v174 offset:18592
	s_waitcnt lgkmcnt(2)
	v_mfma_f32_16x16x32_bf16 v[68:71], v[132:135], v[120:123], v[68:71]
	v_mfma_f32_16x16x32_bf16 v[80:83], v[132:135], v[128:131], v[80:83]
	ds_read_b64_tr_b16 v[132:133], v174 offset:17472
	ds_read_b64_tr_b16 v[134:135], v174 offset:18624
	s_waitcnt lgkmcnt(0)
	v_mfma_f32_16x16x32_bf16 v[84:87], v[132:135], v[120:123], v[84:87]
	v_mfma_f32_16x16x32_bf16 v[88:91], v[132:135], v[128:131], v[88:91]
	ds_read_b64_tr_b16 v[132:133], v174 offset:17504
	ds_read_b64_tr_b16 v[134:135], v174 offset:18656
	s_waitcnt lgkmcnt(0)
	v_mfma_f32_16x16x32_bf16 v[52:55], v[132:135], v[120:123], v[52:55]
	v_mfma_f32_16x16x32_bf16 v[56:59], v[132:135], v[128:131], v[56:59]
	ds_read_b64_tr_b16 v[132:133], v175 offset:17408
	ds_read_b64_tr_b16 v[134:135], v175 offset:18560
	v_mfma_f32_16x16x32_bf16 v[64:67], v[136:139], v[120:123], v[64:67]
	v_mfma_f32_16x16x32_bf16 v[76:79], v[136:139], v[128:131], v[76:79]
	s_waitcnt lgkmcnt(0)
	v_mfma_f32_16x16x32_bf16 v[136:139], v[132:135], v[120:123], v[92:95]
	s_nop 2
	ds_read_b64_tr_b16 v[92:93], v176 offset:17408
	ds_read_b64_tr_b16 v[94:95], v176 offset:18560
	s_waitcnt lgkmcnt(0)
	v_mfma_f32_16x16x32_bf16 v[200:203], v[92:95], v[128:131], v[72:75]
	s_nop 2
	ds_read_b64_tr_b16 v[72:73], v177 offset:17408
	ds_read_b64_tr_b16 v[74:75], v177 offset:18560
	s_waitcnt lgkmcnt(0)
	v_mfma_f32_16x16x32_bf16 v[204:207], v[72:75], v[120:123], v[108:111]
	v_mfma_f32_16x16x32_bf16 v[208:211], v[72:75], v[128:131], v[112:115]
	ds_read_b64_tr_b16 v[72:73], v192 offset:17408
	ds_read_b64_tr_b16 v[74:75], v192 offset:18560
	v_mfma_f32_16x16x32_bf16 v[60:63], v[92:95], v[120:123], v[60:63]
	v_mfma_f32_16x16x32_bf16 v[132:135], v[132:135], v[128:131], v[96:99]
	s_waitcnt lgkmcnt(0)
	v_mfma_f32_16x16x32_bf16 v[120:123], v[72:75], v[120:123], v[100:103]
	v_mfma_f32_16x16x32_bf16 v[128:131], v[72:75], v[128:131], v[104:107]
	ds_read_b64_tr_b16 v[74:75], v174 offset:27776
	ds_read_b64_tr_b16 v[72:73], v174 offset:26624
	ds_read_b64_tr_b16 v[92:93], v174 offset:26656
	ds_read_b64_tr_b16 v[94:95], v174 offset:27808
	s_add_i32 s45, s45, 2
	s_cmp_ge_u32 s47, s43
	s_waitcnt lgkmcnt(2)
	v_mfma_f32_16x16x32_bf16 v[108:111], v[72:75], v[124:127], v[80:83]
	v_mfma_f32_16x16x32_bf16 v[112:115], v[72:75], v[116:119], v[68:71]
	s_waitcnt lgkmcnt(0)
	v_mfma_f32_16x16x32_bf16 v[104:107], v[92:95], v[116:119], v[64:67]
	s_nop 2
	ds_read_b64_tr_b16 v[64:65], v174 offset:26688
	ds_read_b64_tr_b16 v[66:67], v174 offset:27840
	v_mfma_f32_16x16x32_bf16 v[100:103], v[92:95], v[124:127], v[76:79]
	s_waitcnt lgkmcnt(0)
	v_mfma_f32_16x16x32_bf16 v[96:99], v[64:67], v[116:119], v[84:87]
	v_mfma_f32_16x16x32_bf16 v[92:95], v[64:67], v[124:127], v[88:91]
	ds_read_b64_tr_b16 v[64:65], v174 offset:26720
	ds_read_b64_tr_b16 v[66:67], v174 offset:27872
	s_waitcnt lgkmcnt(0)
	v_mfma_f32_16x16x32_bf16 v[88:91], v[64:67], v[116:119], v[52:55]
	s_nop 2
	ds_read_b64_tr_b16 v[52:53], v175 offset:26624
	ds_read_b64_tr_b16 v[54:55], v175 offset:27776
	s_waitcnt lgkmcnt(0)
	v_mfma_f32_16x16x32_bf16 v[80:83], v[52:55], v[116:119], v[136:139]
	v_mfma_f32_16x16x32_bf16 v[76:79], v[52:55], v[124:127], v[132:135]
	ds_read_b64_tr_b16 v[52:53], v176 offset:26624
	ds_read_b64_tr_b16 v[54:55], v176 offset:27776
	s_waitcnt lgkmcnt(0)
	v_mfma_f32_16x16x32_bf16 v[72:75], v[52:55], v[116:119], v[60:63]
	v_mfma_f32_16x16x32_bf16 v[68:71], v[52:55], v[124:127], v[200:203]
	ds_read_b64_tr_b16 v[52:53], v177 offset:26624
	ds_read_b64_tr_b16 v[54:55], v177 offset:27776
	v_mfma_f32_16x16x32_bf16 v[84:87], v[64:67], v[124:127], v[56:59]
	s_waitcnt lgkmcnt(0)
	v_mfma_f32_16x16x32_bf16 v[64:67], v[52:55], v[116:119], v[204:207]
	v_mfma_f32_16x16x32_bf16 v[56:59], v[52:55], v[124:127], v[208:211]
	ds_read_b64_tr_b16 v[52:53], v192 offset:26624
	ds_read_b64_tr_b16 v[54:55], v192 offset:27776
	s_waitcnt lgkmcnt(0)
	v_mfma_f32_16x16x32_bf16 v[60:63], v[52:55], v[116:119], v[120:123]
	v_mfma_f32_16x16x32_bf16 v[52:55], v[52:55], v[124:127], v[128:131]
	s_cbranch_scc1 .LBB0_1054
